# v15 + non-temporal (nt) cache hint on the residual loads of the coalesced w_out / mlp2 epilogues
# speedup vs baseline: 1.0093x; 1.0093x over previous
;     DI void operator()(const f32x4 (&acc)[2][2][4][2], const Unit& u, int wr, int wc, int fr, int fq) const {
;     ...
;         const int rin = wr * 64 + fr, col0 = u.pn * BM + wc * 32 + 8 * fq;
; #pragma unroll
;         for (int bj = 0; bj < 2; ++bj) { const int col = col0 + bj * HALF; const f32x4 g0 = *(const f32x4*)(garow + col), g1 = *(const f32x4*)(garow + col + 4);
; #pragma unroll
;             for (int ai = 0; ai < 2; ++ai)
; #pragma unroll
;                 for (int m = 0; m < 4; ++m) { const size_t off = (size_t)(rin + ai * HALF + m * 16) * D + col;
;                     if (u.split) { float* sp = (float*)(P.ws + WS_SLAB) + ((size_t)u.sl * (NB * CTX) + (size_t)b * CTX) * D + off;
;                         *(f32x4*)sp = g0 * acc[ai][bj][m][0]; *(f32x4*)(sp + 4) = g1 * acc[ai][bj][m][1]; }
;                     else { const f32x4 x0 = *(const f32x4*)(rbase + off), x1 = *(const f32x4*)(rbase + off + 4);
;                         *(f32x4*)(dbase + off) = x0 + g0 * acc[ai][bj][m][0]; *(f32x4*)(dbase + off + 4) = x1 + g1 * acc[ai][bj][m][1]; } } }
.Lepi_wo_fast:
	v_mbcnt_lo_u32_b32 v204, -1, 0
	v_mbcnt_hi_u32_b32 v204, -1, v204
	v_readfirstlane_b32 s78, v182
	v_readfirstlane_b32 s79, v154
	v_readfirstlane_b32 s80, v178
	v_readfirstlane_b32 s81, v179
	v_readlane_b32 s82, v253, 14
	v_and_b32_e32 v211, 7, v204
	v_lshrrev_b32_e32 v205, 4, v204
	v_lshlrev_b32_e32 v205, 1, v205
	v_xor_b32_e32 v205, v205, v211
	v_lshlrev_b32_e32 v205, 4, v205
	v_lshl_or_b32 v205, v211, 7, v205
	v_bfe_u32 v206, v204, 3, 1
	v_lshl_or_b32 v205, v206, 13, v205
	v_lshrrev_b32_e32 v207, 3, v204
	v_xor_b32_e32 v209, v211, v207
	v_lshlrev_b32_e32 v209, 4, v209
	v_lshlrev_b32_e32 v210, 4, v211
	v_lshl_or_b32 v208, v207, 12, v210
	v_lshl_or_b32 v207, v207, 7, v209
	s_add_i32 s82, s82, 0xc000
	v_add_u32_e32 v205, s82, v205
	v_xor_b32_e32 v206, 16, v205
	v_add_u32_e32 v207, s82, v207
	v_add_u32_e32 v209, 0x8000, v208
	s_add_i32 s78, s78, s79
	s_lshl_b32 s78, s78, 2
	s_add_u32 s74, s18, s78
	s_addc_u32 s75, s19, 0
	s_add_u32 s76, s16, s78
	s_addc_u32 s77, s17, 0
	global_load_dwordx4 v[212:215], v210, s[80:81]
	global_load_dwordx4 v[216:219], v210, s[80:81] offset:512
	global_load_dwordx4 v[236:239], v208, s[74:75] nt
	global_load_dwordx4 v[240:243], v209, s[74:75] nt
	global_load_dwordx4 v[244:247], v208, s[74:75] offset:512 nt
	global_load_dwordx4 v[192:195], v209, s[74:75] offset:512 nt
	s_add_u32 s74, s74, 0x10000
	s_addc_u32 s75, s75, 0
	global_load_dwordx4 v[196:199], v208, s[74:75] nt
	global_load_dwordx4 v[186:189], v209, s[74:75] nt
	ds_write_b128 v205, v[126:129]
	ds_write_b128 v206, v[122:125]
	ds_read_b128 v[220:223], v207
	ds_read_b128 v[224:227], v207 offset:8192
	ds_write_b128 v205, v[60:63]
	ds_write_b128 v206, v[56:59]
	ds_read_b128 v[228:231], v207
	ds_read_b128 v[232:235], v207 offset:8192
	s_waitcnt vmcnt(5) lgkmcnt(5)
	v_pk_fma_f32 v[220:221], v[220:221], v[212:213], v[236:237]
	v_pk_fma_f32 v[222:223], v[222:223], v[214:215], v[238:239]
	global_store_dwordx4 v208, v[220:223], s[76:77]
	global_load_dwordx4 v[236:239], v208, s[74:75] offset:512 nt
	s_waitcnt vmcnt(6) lgkmcnt(4)
	v_pk_fma_f32 v[224:225], v[224:225], v[212:213], v[240:241]
	v_pk_fma_f32 v[226:227], v[226:227], v[214:215], v[242:243]
	global_store_dwordx4 v209, v[224:227], s[76:77]
	global_load_dwordx4 v[240:243], v209, s[74:75] offset:512 nt
	ds_write_b128 v205, v[118:121]
	ds_write_b128 v206, v[114:117]
	ds_read_b128 v[220:223], v207
	ds_read_b128 v[224:227], v207 offset:8192
	s_waitcnt vmcnt(7) lgkmcnt(5)
	v_pk_fma_f32 v[228:229], v[228:229], v[216:217], v[244:245]
	v_pk_fma_f32 v[230:231], v[230:231], v[218:219], v[246:247]
	global_store_dwordx4 v208, v[228:231], s[76:77] offset:512
	s_add_u32 s74, s74, 0x10000
	s_addc_u32 s75, s75, 0
	global_load_dwordx4 v[244:247], v208, s[74:75] nt
	s_waitcnt vmcnt(8) lgkmcnt(4)
	v_pk_fma_f32 v[232:233], v[232:233], v[216:217], v[192:193]
	v_pk_fma_f32 v[234:235], v[234:235], v[218:219], v[194:195]
	global_store_dwordx4 v209, v[232:235], s[76:77] offset:512
	global_load_dwordx4 v[192:195], v209, s[74:75] nt
	ds_write_b128 v205, v[52:55]
	ds_write_b128 v206, v[48:51]
	ds_read_b128 v[228:231], v207
	ds_read_b128 v[232:235], v207 offset:8192
	s_waitcnt vmcnt(9) lgkmcnt(5)
	v_pk_fma_f32 v[220:221], v[220:221], v[212:213], v[196:197]
	v_pk_fma_f32 v[222:223], v[222:223], v[214:215], v[198:199]
	s_add_u32 s76, s76, 0x10000
	s_addc_u32 s77, s77, 0
	global_store_dwordx4 v208, v[220:223], s[76:77]
	global_load_dwordx4 v[196:199], v208, s[74:75] offset:512 nt
	s_waitcnt vmcnt(10) lgkmcnt(4)
	v_pk_fma_f32 v[224:225], v[224:225], v[212:213], v[186:187]
	v_pk_fma_f32 v[226:227], v[226:227], v[214:215], v[188:189]
	global_store_dwordx4 v209, v[224:227], s[76:77]
	global_load_dwordx4 v[186:189], v209, s[74:75] offset:512 nt
	ds_write_b128 v205, v[108:111]
	ds_write_b128 v206, v[104:107]
	ds_read_b128 v[220:223], v207
	ds_read_b128 v[224:227], v207 offset:8192
	s_waitcnt vmcnt(10) lgkmcnt(5)
	v_pk_fma_f32 v[228:229], v[228:229], v[216:217], v[236:237]
	v_pk_fma_f32 v[230:231], v[230:231], v[218:219], v[238:239]
	global_store_dwordx4 v208, v[228:231], s[76:77] offset:512
	s_add_u32 s74, s74, 0x10000
	s_addc_u32 s75, s75, 0
	global_load_dwordx4 v[236:239], v208, s[74:75] nt
	s_waitcnt vmcnt(10) lgkmcnt(4)
	v_pk_fma_f32 v[232:233], v[232:233], v[216:217], v[240:241]
	v_pk_fma_f32 v[234:235], v[234:235], v[218:219], v[242:243]
	global_store_dwordx4 v209, v[232:235], s[76:77] offset:512
	global_load_dwordx4 v[240:243], v209, s[74:75] nt
	ds_write_b128 v205, v[44:47]
	ds_write_b128 v206, v[40:43]
	ds_read_b128 v[228:231], v207
	ds_read_b128 v[232:235], v207 offset:8192
	s_waitcnt vmcnt(10) lgkmcnt(5)
	v_pk_fma_f32 v[220:221], v[220:221], v[212:213], v[244:245]
	v_pk_fma_f32 v[222:223], v[222:223], v[214:215], v[246:247]
	s_add_u32 s76, s76, 0x10000
	s_addc_u32 s77, s77, 0
	global_store_dwordx4 v208, v[220:223], s[76:77]
	global_load_dwordx4 v[244:247], v208, s[74:75] offset:512 nt
	s_waitcnt vmcnt(10) lgkmcnt(4)
	v_pk_fma_f32 v[224:225], v[224:225], v[212:213], v[192:193]
	v_pk_fma_f32 v[226:227], v[226:227], v[214:215], v[194:195]
	global_store_dwordx4 v209, v[224:227], s[76:77]
	global_load_dwordx4 v[192:195], v209, s[74:75] offset:512 nt
	ds_write_b128 v205, v[100:103]
	ds_write_b128 v206, v[96:99]
	ds_read_b128 v[220:223], v207
	ds_read_b128 v[224:227], v207 offset:8192
	s_waitcnt vmcnt(10) lgkmcnt(5)
	v_pk_fma_f32 v[228:229], v[228:229], v[216:217], v[196:197]
	v_pk_fma_f32 v[230:231], v[230:231], v[218:219], v[198:199]
	global_store_dwordx4 v208, v[228:231], s[76:77] offset:512
	s_add_u32 s74, s74, 0x50000
	s_addc_u32 s75, s75, 0
	global_load_dwordx4 v[196:199], v208, s[74:75] nt
	s_waitcnt vmcnt(10) lgkmcnt(4)
;     DI void operator()(const f32x4 (&acc)[2][2][4][2], const Unit& u, int wr, int wc, int fr, int fq) const {
;     ...
;             for (int ai = 0; ai < 2; ++ai)
; #pragma unroll
;                 for (int m = 0; m < 4; ++m) { const size_t off = (size_t)(rin + ai * HALF + m * 16) * D + col;
;                     if (u.split) { float* sp = (float*)(P.ws + WS_SLAB) + ((size_t)u.sl * (NB * CTX) + (size_t)b * CTX) * D + off;
;                         *(f32x4*)sp = g0 * acc[ai][bj][m][0]; *(f32x4*)(sp + 4) = g1 * acc[ai][bj][m][1]; }
;                     else { const f32x4 x0 = *(const f32x4*)(rbase + off), x1 = *(const f32x4*)(rbase + off + 4);
;                         *(f32x4*)(dbase + off) = x0 + g0 * acc[ai][bj][m][0]; *(f32x4*)(dbase + off + 4) = x1 + g1 * acc[ai][bj][m][1]; } } }
	v_pk_fma_f32 v[232:233], v[232:233], v[216:217], v[186:187]
	v_pk_fma_f32 v[234:235], v[234:235], v[218:219], v[188:189]
	global_store_dwordx4 v209, v[232:235], s[76:77] offset:512
	global_load_dwordx4 v[186:189], v209, s[74:75] nt
	ds_write_b128 v205, v[36:39]
	ds_write_b128 v206, v[32:35]
	ds_read_b128 v[228:231], v207
	ds_read_b128 v[232:235], v207 offset:8192
	s_waitcnt vmcnt(10) lgkmcnt(5)
	v_pk_fma_f32 v[220:221], v[220:221], v[212:213], v[236:237]
	v_pk_fma_f32 v[222:223], v[222:223], v[214:215], v[238:239]
	s_add_u32 s76, s76, 0x10000
	s_addc_u32 s77, s77, 0
	global_store_dwordx4 v208, v[220:223], s[76:77]
	global_load_dwordx4 v[236:239], v208, s[74:75] offset:512 nt
	s_waitcnt vmcnt(10) lgkmcnt(4)
	v_pk_fma_f32 v[224:225], v[224:225], v[212:213], v[240:241]
	v_pk_fma_f32 v[226:227], v[226:227], v[214:215], v[242:243]
	global_store_dwordx4 v209, v[224:227], s[76:77]
	global_load_dwordx4 v[240:243], v209, s[74:75] offset:512 nt
	ds_write_b128 v205, v[92:95]
	ds_write_b128 v206, v[88:91]
	ds_read_b128 v[220:223], v207
	ds_read_b128 v[224:227], v207 offset:8192
	s_waitcnt vmcnt(10) lgkmcnt(5)
	v_pk_fma_f32 v[228:229], v[228:229], v[216:217], v[244:245]
	v_pk_fma_f32 v[230:231], v[230:231], v[218:219], v[246:247]
	global_store_dwordx4 v208, v[228:231], s[76:77] offset:512
	s_add_u32 s74, s74, 0x10000
	s_addc_u32 s75, s75, 0
	global_load_dwordx4 v[244:247], v208, s[74:75] nt
	s_waitcnt vmcnt(10) lgkmcnt(4)
	v_pk_fma_f32 v[232:233], v[232:233], v[216:217], v[192:193]
	v_pk_fma_f32 v[234:235], v[234:235], v[218:219], v[194:195]
	global_store_dwordx4 v209, v[232:235], s[76:77] offset:512
	global_load_dwordx4 v[192:195], v209, s[74:75] nt
	ds_write_b128 v205, v[28:31]
	ds_write_b128 v206, v[24:27]
	ds_read_b128 v[228:231], v207
	ds_read_b128 v[232:235], v207 offset:8192
	s_waitcnt vmcnt(10) lgkmcnt(5)
	v_pk_fma_f32 v[220:221], v[220:221], v[212:213], v[196:197]
	v_pk_fma_f32 v[222:223], v[222:223], v[214:215], v[198:199]
	s_add_u32 s76, s76, 0x50000
	s_addc_u32 s77, s77, 0
	global_store_dwordx4 v208, v[220:223], s[76:77]
	global_load_dwordx4 v[196:199], v208, s[74:75] offset:512 nt
	s_waitcnt vmcnt(10) lgkmcnt(4)
	v_pk_fma_f32 v[224:225], v[224:225], v[212:213], v[186:187]
	v_pk_fma_f32 v[226:227], v[226:227], v[214:215], v[188:189]
	global_store_dwordx4 v209, v[224:227], s[76:77]
	global_load_dwordx4 v[186:189], v209, s[74:75] offset:512 nt
	ds_write_b128 v205, v[84:87]
	ds_write_b128 v206, v[80:83]
	ds_read_b128 v[220:223], v207
	ds_read_b128 v[224:227], v207 offset:8192
	s_waitcnt vmcnt(10) lgkmcnt(5)
	v_pk_fma_f32 v[228:229], v[228:229], v[216:217], v[236:237]
	v_pk_fma_f32 v[230:231], v[230:231], v[218:219], v[238:239]
	global_store_dwordx4 v208, v[228:231], s[76:77] offset:512
	s_add_u32 s74, s74, 0x10000
	s_addc_u32 s75, s75, 0
	global_load_dwordx4 v[236:239], v208, s[74:75] nt
	s_waitcnt vmcnt(10) lgkmcnt(4)
	v_pk_fma_f32 v[232:233], v[232:233], v[216:217], v[240:241]
	v_pk_fma_f32 v[234:235], v[234:235], v[218:219], v[242:243]
	global_store_dwordx4 v209, v[232:235], s[76:77] offset:512
	global_load_dwordx4 v[240:243], v209, s[74:75] nt
	ds_write_b128 v205, v[20:23]
	ds_write_b128 v206, v[16:19]
	ds_read_b128 v[228:231], v207
	ds_read_b128 v[232:235], v207 offset:8192
	s_waitcnt vmcnt(10) lgkmcnt(5)
	v_pk_fma_f32 v[220:221], v[220:221], v[212:213], v[244:245]
	v_pk_fma_f32 v[222:223], v[222:223], v[214:215], v[246:247]
	s_add_u32 s76, s76, 0x10000
	s_addc_u32 s77, s77, 0
	global_store_dwordx4 v208, v[220:223], s[76:77]
	global_load_dwordx4 v[244:247], v208, s[74:75] offset:512 nt
	s_waitcnt vmcnt(10) lgkmcnt(4)
	v_pk_fma_f32 v[224:225], v[224:225], v[212:213], v[192:193]
	v_pk_fma_f32 v[226:227], v[226:227], v[214:215], v[194:195]
	global_store_dwordx4 v209, v[224:227], s[76:77]
	global_load_dwordx4 v[192:195], v209, s[74:75] offset:512 nt
	ds_write_b128 v205, v[76:79]
	ds_write_b128 v206, v[72:75]
	ds_read_b128 v[220:223], v207
	ds_read_b128 v[224:227], v207 offset:8192
	s_waitcnt vmcnt(10) lgkmcnt(5)
	v_pk_fma_f32 v[228:229], v[228:229], v[216:217], v[196:197]
	v_pk_fma_f32 v[230:231], v[230:231], v[218:219], v[198:199]
	global_store_dwordx4 v208, v[228:231], s[76:77] offset:512
	s_add_u32 s74, s74, 0x10000
	s_addc_u32 s75, s75, 0
	global_load_dwordx4 v[196:199], v208, s[74:75] nt
	s_waitcnt vmcnt(10) lgkmcnt(4)
	v_pk_fma_f32 v[232:233], v[232:233], v[216:217], v[186:187]
	v_pk_fma_f32 v[234:235], v[234:235], v[218:219], v[188:189]
	global_store_dwordx4 v209, v[232:235], s[76:77] offset:512
	global_load_dwordx4 v[186:189], v209, s[74:75] nt
	ds_write_b128 v205, v[12:15]
	ds_write_b128 v206, v[8:11]
	ds_read_b128 v[228:231], v207
	ds_read_b128 v[232:235], v207 offset:8192
	s_waitcnt vmcnt(10) lgkmcnt(5)
	v_pk_fma_f32 v[220:221], v[220:221], v[212:213], v[236:237]
	v_pk_fma_f32 v[222:223], v[222:223], v[214:215], v[238:239]
	s_add_u32 s76, s76, 0x10000
	s_addc_u32 s77, s77, 0
	global_store_dwordx4 v208, v[220:223], s[76:77]
	global_load_dwordx4 v[236:239], v208, s[74:75] offset:512 nt
	s_waitcnt vmcnt(10) lgkmcnt(4)
	v_pk_fma_f32 v[224:225], v[224:225], v[212:213], v[240:241]
	v_pk_fma_f32 v[226:227], v[226:227], v[214:215], v[242:243]
	global_store_dwordx4 v209, v[224:227], s[76:77]
	global_load_dwordx4 v[240:243], v209, s[74:75] offset:512 nt
	ds_write_b128 v205, v[68:71]
	ds_write_b128 v206, v[64:67]
	ds_read_b128 v[220:223], v207
	ds_read_b128 v[224:227], v207 offset:8192
	s_waitcnt vmcnt(10) lgkmcnt(5)
	v_pk_fma_f32 v[228:229], v[228:229], v[216:217], v[244:245]
	v_pk_fma_f32 v[230:231], v[230:231], v[218:219], v[246:247]
	global_store_dwordx4 v208, v[228:231], s[76:77] offset:512
	s_waitcnt vmcnt(9) lgkmcnt(4)
	v_pk_fma_f32 v[232:233], v[232:233], v[216:217], v[192:193]
	v_pk_fma_f32 v[234:235], v[234:235], v[218:219], v[194:195]
	global_store_dwordx4 v209, v[232:235], s[76:77] offset:512
	ds_write_b128 v205, v[4:7]
	ds_write_b128 v206, v[0:3]
	ds_read_b128 v[228:231], v207
	ds_read_b128 v[232:235], v207 offset:8192
	s_waitcnt vmcnt(8) lgkmcnt(5)
	v_pk_fma_f32 v[220:221], v[220:221], v[212:213], v[196:197]
	v_pk_fma_f32 v[222:223], v[222:223], v[214:215], v[198:199]
	s_add_u32 s76, s76, 0x10000
	s_addc_u32 s77, s77, 0
	global_store_dwordx4 v208, v[220:223], s[76:77]
	s_waitcnt vmcnt(7) lgkmcnt(4)
	v_pk_fma_f32 v[224:225], v[224:225], v[212:213], v[186:187]
	v_pk_fma_f32 v[226:227], v[226:227], v[214:215], v[188:189]
	global_store_dwordx4 v209, v[224:227], s[76:77]
	s_waitcnt vmcnt(6) lgkmcnt(1)
	v_pk_fma_f32 v[228:229], v[228:229], v[216:217], v[236:237]
	v_pk_fma_f32 v[230:231], v[230:231], v[218:219], v[238:239]
	global_store_dwordx4 v208, v[228:231], s[76:77] offset:512
	s_waitcnt vmcnt(5) lgkmcnt(0)
	v_pk_fma_f32 v[232:233], v[232:233], v[216:217], v[240:241]
	v_pk_fma_f32 v[234:235], v[234:235], v[218:219], v[242:243]
	global_store_dwordx4 v209, v[232:235], s[76:77] offset:512
	s_andn2_b64 vcc, exec, s[8:9]
	s_mov_b64 s[0:1], -1
	s_cbranch_vccnz .LBB0_686
	s_branch .Lepi_wo_after

;     DI void operator()(const f32x4 (&acc)[2][2][4][2], const Unit& u, int wr, int wc, int fr, int fq) const {
;     ...
;         const int rin = wr * 64 + fr, col0 = u.pn * BM + wc * 32 + 8 * fq;
; #pragma unroll
;         for (int bj = 0; bj < 2; ++bj) { const int col = col0 + bj * HALF; const f32x4 g0 = *(const f32x4*)(garow + col), g1 = *(const f32x4*)(garow + col + 4);
; #pragma unroll
;             for (int ai = 0; ai < 2; ++ai)
; #pragma unroll
;                 for (int m = 0; m < 4; ++m) { const size_t off = (size_t)(rin + ai * HALF + m * 16) * D + col;
;                     if (u.split) { float* sp = (float*)(P.ws + WS_SLAB) + ((size_t)u.sl * (NB * CTX) + (size_t)b * CTX) * D + off;
;                         *(f32x4*)sp = g0 * acc[ai][bj][m][0]; *(f32x4*)(sp + 4) = g1 * acc[ai][bj][m][1]; }
;                     else { const f32x4 x0 = *(const f32x4*)(rbase + off), x1 = *(const f32x4*)(rbase + off + 4);
;                         *(f32x4*)(dbase + off) = x0 + g0 * acc[ai][bj][m][0]; *(f32x4*)(dbase + off + 4) = x1 + g1 * acc[ai][bj][m][1]; } } }
.Lepi_m2_fast:
	v_mbcnt_lo_u32_b32 v206, -1, 0
	v_mbcnt_hi_u32_b32 v206, -1, v206
	v_readfirstlane_b32 s78, v184
	v_readfirstlane_b32 s79, v154
	v_readfirstlane_b32 s80, v180
	v_readfirstlane_b32 s81, v181
	v_readlane_b32 s82, v253, 14
	v_readfirstlane_b32 s74, v186
	v_readfirstlane_b32 s75, v187
	v_readfirstlane_b32 s76, v174
	v_readfirstlane_b32 s77, v175
	v_and_b32_e32 v213, 7, v206
	v_lshrrev_b32_e32 v207, 4, v206
	v_lshlrev_b32_e32 v207, 1, v207
	v_xor_b32_e32 v207, v207, v213
	v_lshlrev_b32_e32 v207, 4, v207
	v_lshl_or_b32 v207, v213, 7, v207
	v_bfe_u32 v208, v206, 3, 1
	v_lshl_or_b32 v207, v208, 13, v207
	v_lshrrev_b32_e32 v209, 3, v206
	v_xor_b32_e32 v211, v213, v209
	v_lshlrev_b32_e32 v211, 4, v211
	v_lshlrev_b32_e32 v212, 4, v213
	v_lshl_or_b32 v210, v209, 12, v212
	v_lshl_or_b32 v209, v209, 7, v211
	s_add_i32 s82, s82, 0xc000
	v_add_u32_e32 v207, s82, v207
	v_xor_b32_e32 v208, 16, v207
	v_add_u32_e32 v209, s82, v209
	v_add_u32_e32 v211, 0x8000, v210
	s_add_i32 s78, s78, s79
	s_lshl_b32 s78, s78, 2
	s_add_u32 s74, s74, s78
	s_addc_u32 s75, s75, 0
	s_add_u32 s76, s76, s78
	s_addc_u32 s77, s77, 0
	global_load_dwordx4 v[214:217], v212, s[80:81]
	global_load_dwordx4 v[218:221], v212, s[80:81] offset:512
	global_load_dwordx4 v[238:241], v210, s[74:75] nt
	global_load_dwordx4 v[242:245], v211, s[74:75] nt
	global_load_dwordx4 v[246:249], v210, s[74:75] offset:512 nt
	global_load_dwordx4 v[192:195], v211, s[74:75] offset:512 nt
	s_add_u32 s74, s74, 0x10000
	s_addc_u32 s75, s75, 0
	global_load_dwordx4 v[196:199], v210, s[74:75] nt
	global_load_dwordx4 v[186:189], v211, s[74:75] nt
	ds_write_b128 v207, v[126:129]
	ds_write_b128 v208, v[122:125]
	ds_read_b128 v[222:225], v209
	ds_read_b128 v[226:229], v209 offset:8192
	ds_write_b128 v207, v[60:63]
	ds_write_b128 v208, v[56:59]
	ds_read_b128 v[230:233], v209
	ds_read_b128 v[234:237], v209 offset:8192
	s_waitcnt vmcnt(5) lgkmcnt(5)
	v_pk_fma_f32 v[222:223], v[222:223], v[214:215], v[238:239]
	v_pk_fma_f32 v[224:225], v[224:225], v[216:217], v[240:241]
	global_store_dwordx4 v210, v[222:225], s[76:77]
	global_load_dwordx4 v[238:241], v210, s[74:75] offset:512 nt
	s_waitcnt vmcnt(6) lgkmcnt(4)
	v_pk_fma_f32 v[226:227], v[226:227], v[214:215], v[242:243]
	v_pk_fma_f32 v[228:229], v[228:229], v[216:217], v[244:245]
	global_store_dwordx4 v211, v[226:229], s[76:77]
	global_load_dwordx4 v[242:245], v211, s[74:75] offset:512 nt
	ds_write_b128 v207, v[118:121]
	ds_write_b128 v208, v[114:117]
	ds_read_b128 v[222:225], v209
	ds_read_b128 v[226:229], v209 offset:8192
	s_waitcnt vmcnt(7) lgkmcnt(5)
	v_pk_fma_f32 v[230:231], v[230:231], v[218:219], v[246:247]
	v_pk_fma_f32 v[232:233], v[232:233], v[220:221], v[248:249]
	global_store_dwordx4 v210, v[230:233], s[76:77] offset:512
	s_add_u32 s74, s74, 0x10000
	s_addc_u32 s75, s75, 0
	global_load_dwordx4 v[246:249], v210, s[74:75] nt
	s_waitcnt vmcnt(8) lgkmcnt(4)
	v_pk_fma_f32 v[234:235], v[234:235], v[218:219], v[192:193]
	v_pk_fma_f32 v[236:237], v[236:237], v[220:221], v[194:195]
	global_store_dwordx4 v211, v[234:237], s[76:77] offset:512
	global_load_dwordx4 v[192:195], v211, s[74:75] nt
	ds_write_b128 v207, v[52:55]
	ds_write_b128 v208, v[48:51]
	ds_read_b128 v[230:233], v209
	ds_read_b128 v[234:237], v209 offset:8192
	s_waitcnt vmcnt(9) lgkmcnt(5)
	v_pk_fma_f32 v[222:223], v[222:223], v[214:215], v[196:197]
	v_pk_fma_f32 v[224:225], v[224:225], v[216:217], v[198:199]
	s_add_u32 s76, s76, 0x10000
	s_addc_u32 s77, s77, 0
	global_store_dwordx4 v210, v[222:225], s[76:77]
	global_load_dwordx4 v[196:199], v210, s[74:75] offset:512 nt
	s_waitcnt vmcnt(10) lgkmcnt(4)
	v_pk_fma_f32 v[226:227], v[226:227], v[214:215], v[186:187]
	v_pk_fma_f32 v[228:229], v[228:229], v[216:217], v[188:189]
	global_store_dwordx4 v211, v[226:229], s[76:77]
	global_load_dwordx4 v[186:189], v211, s[74:75] offset:512 nt
	ds_write_b128 v207, v[108:111]
	ds_write_b128 v208, v[104:107]
	ds_read_b128 v[222:225], v209
	ds_read_b128 v[226:229], v209 offset:8192
	s_waitcnt vmcnt(10) lgkmcnt(5)
	v_pk_fma_f32 v[230:231], v[230:231], v[218:219], v[238:239]
	v_pk_fma_f32 v[232:233], v[232:233], v[220:221], v[240:241]
	global_store_dwordx4 v210, v[230:233], s[76:77] offset:512
	s_add_u32 s74, s74, 0x10000
	s_addc_u32 s75, s75, 0
	global_load_dwordx4 v[238:241], v210, s[74:75] nt
	s_waitcnt vmcnt(10) lgkmcnt(4)
	v_pk_fma_f32 v[234:235], v[234:235], v[218:219], v[242:243]
	v_pk_fma_f32 v[236:237], v[236:237], v[220:221], v[244:245]
	global_store_dwordx4 v211, v[234:237], s[76:77] offset:512
	global_load_dwordx4 v[242:245], v211, s[74:75] nt
	ds_write_b128 v207, v[44:47]
	ds_write_b128 v208, v[40:43]
	ds_read_b128 v[230:233], v209
	ds_read_b128 v[234:237], v209 offset:8192
	s_waitcnt vmcnt(10) lgkmcnt(5)
	v_pk_fma_f32 v[222:223], v[222:223], v[214:215], v[246:247]
	v_pk_fma_f32 v[224:225], v[224:225], v[216:217], v[248:249]
	s_add_u32 s76, s76, 0x10000
	s_addc_u32 s77, s77, 0
	global_store_dwordx4 v210, v[222:225], s[76:77]
	global_load_dwordx4 v[246:249], v210, s[74:75] offset:512 nt
	s_waitcnt vmcnt(10) lgkmcnt(4)
	v_pk_fma_f32 v[226:227], v[226:227], v[214:215], v[192:193]
	v_pk_fma_f32 v[228:229], v[228:229], v[216:217], v[194:195]
	global_store_dwordx4 v211, v[226:229], s[76:77]
	global_load_dwordx4 v[192:195], v211, s[74:75] offset:512 nt
	ds_write_b128 v207, v[100:103]
	ds_write_b128 v208, v[96:99]
	ds_read_b128 v[222:225], v209
	ds_read_b128 v[226:229], v209 offset:8192
	s_waitcnt vmcnt(10) lgkmcnt(5)
	v_pk_fma_f32 v[230:231], v[230:231], v[218:219], v[196:197]
	v_pk_fma_f32 v[232:233], v[232:233], v[220:221], v[198:199]
	global_store_dwordx4 v210, v[230:233], s[76:77] offset:512
	s_add_u32 s74, s74, 0x50000
	s_addc_u32 s75, s75, 0
	global_load_dwordx4 v[196:199], v210, s[74:75] nt
	s_waitcnt vmcnt(10) lgkmcnt(4)
;     DI void operator()(const f32x4 (&acc)[2][2][4][2], const Unit& u, int wr, int wc, int fr, int fq) const {
;     ...
;             for (int ai = 0; ai < 2; ++ai)
; #pragma unroll
;                 for (int m = 0; m < 4; ++m) { const size_t off = (size_t)(rin + ai * HALF + m * 16) * D + col;
;                     if (u.split) { float* sp = (float*)(P.ws + WS_SLAB) + ((size_t)u.sl * (NB * CTX) + (size_t)b * CTX) * D + off;
;                         *(f32x4*)sp = g0 * acc[ai][bj][m][0]; *(f32x4*)(sp + 4) = g1 * acc[ai][bj][m][1]; }
;                     else { const f32x4 x0 = *(const f32x4*)(rbase + off), x1 = *(const f32x4*)(rbase + off + 4);
;                         *(f32x4*)(dbase + off) = x0 + g0 * acc[ai][bj][m][0]; *(f32x4*)(dbase + off + 4) = x1 + g1 * acc[ai][bj][m][1]; } } }
	v_pk_fma_f32 v[234:235], v[234:235], v[218:219], v[186:187]
	v_pk_fma_f32 v[236:237], v[236:237], v[220:221], v[188:189]
	global_store_dwordx4 v211, v[234:237], s[76:77] offset:512
	global_load_dwordx4 v[186:189], v211, s[74:75] nt
	ds_write_b128 v207, v[36:39]
	ds_write_b128 v208, v[32:35]
	ds_read_b128 v[230:233], v209
	ds_read_b128 v[234:237], v209 offset:8192
	s_waitcnt vmcnt(10) lgkmcnt(5)
	v_pk_fma_f32 v[222:223], v[222:223], v[214:215], v[238:239]
	v_pk_fma_f32 v[224:225], v[224:225], v[216:217], v[240:241]
	s_add_u32 s76, s76, 0x10000
	s_addc_u32 s77, s77, 0
	global_store_dwordx4 v210, v[222:225], s[76:77]
	global_load_dwordx4 v[238:241], v210, s[74:75] offset:512 nt
	s_waitcnt vmcnt(10) lgkmcnt(4)
	v_pk_fma_f32 v[226:227], v[226:227], v[214:215], v[242:243]
	v_pk_fma_f32 v[228:229], v[228:229], v[216:217], v[244:245]
	global_store_dwordx4 v211, v[226:229], s[76:77]
	global_load_dwordx4 v[242:245], v211, s[74:75] offset:512 nt
	ds_write_b128 v207, v[92:95]
	ds_write_b128 v208, v[88:91]
	ds_read_b128 v[222:225], v209
	ds_read_b128 v[226:229], v209 offset:8192
	s_waitcnt vmcnt(10) lgkmcnt(5)
	v_pk_fma_f32 v[230:231], v[230:231], v[218:219], v[246:247]
	v_pk_fma_f32 v[232:233], v[232:233], v[220:221], v[248:249]
	global_store_dwordx4 v210, v[230:233], s[76:77] offset:512
	s_add_u32 s74, s74, 0x10000
	s_addc_u32 s75, s75, 0
	global_load_dwordx4 v[246:249], v210, s[74:75] nt
	s_waitcnt vmcnt(10) lgkmcnt(4)
	v_pk_fma_f32 v[234:235], v[234:235], v[218:219], v[192:193]
	v_pk_fma_f32 v[236:237], v[236:237], v[220:221], v[194:195]
	global_store_dwordx4 v211, v[234:237], s[76:77] offset:512
	global_load_dwordx4 v[192:195], v211, s[74:75] nt
	ds_write_b128 v207, v[28:31]
	ds_write_b128 v208, v[24:27]
	ds_read_b128 v[230:233], v209
	ds_read_b128 v[234:237], v209 offset:8192
	s_waitcnt vmcnt(10) lgkmcnt(5)
	v_pk_fma_f32 v[222:223], v[222:223], v[214:215], v[196:197]
	v_pk_fma_f32 v[224:225], v[224:225], v[216:217], v[198:199]
	s_add_u32 s76, s76, 0x50000
	s_addc_u32 s77, s77, 0
	global_store_dwordx4 v210, v[222:225], s[76:77]
	global_load_dwordx4 v[196:199], v210, s[74:75] offset:512 nt
	s_waitcnt vmcnt(10) lgkmcnt(4)
	v_pk_fma_f32 v[226:227], v[226:227], v[214:215], v[186:187]
	v_pk_fma_f32 v[228:229], v[228:229], v[216:217], v[188:189]
	global_store_dwordx4 v211, v[226:229], s[76:77]
	global_load_dwordx4 v[186:189], v211, s[74:75] offset:512 nt
	ds_write_b128 v207, v[84:87]
	ds_write_b128 v208, v[80:83]
	ds_read_b128 v[222:225], v209
	ds_read_b128 v[226:229], v209 offset:8192
	s_waitcnt vmcnt(10) lgkmcnt(5)
	v_pk_fma_f32 v[230:231], v[230:231], v[218:219], v[238:239]
	v_pk_fma_f32 v[232:233], v[232:233], v[220:221], v[240:241]
	global_store_dwordx4 v210, v[230:233], s[76:77] offset:512
	s_add_u32 s74, s74, 0x10000
	s_addc_u32 s75, s75, 0
	global_load_dwordx4 v[238:241], v210, s[74:75] nt
	s_waitcnt vmcnt(10) lgkmcnt(4)
	v_pk_fma_f32 v[234:235], v[234:235], v[218:219], v[242:243]
	v_pk_fma_f32 v[236:237], v[236:237], v[220:221], v[244:245]
	global_store_dwordx4 v211, v[234:237], s[76:77] offset:512
	global_load_dwordx4 v[242:245], v211, s[74:75] nt
	ds_write_b128 v207, v[20:23]
	ds_write_b128 v208, v[16:19]
	ds_read_b128 v[230:233], v209
	ds_read_b128 v[234:237], v209 offset:8192
	s_waitcnt vmcnt(10) lgkmcnt(5)
	v_pk_fma_f32 v[222:223], v[222:223], v[214:215], v[246:247]
	v_pk_fma_f32 v[224:225], v[224:225], v[216:217], v[248:249]
	s_add_u32 s76, s76, 0x10000
	s_addc_u32 s77, s77, 0
	global_store_dwordx4 v210, v[222:225], s[76:77]
	global_load_dwordx4 v[246:249], v210, s[74:75] offset:512 nt
	s_waitcnt vmcnt(10) lgkmcnt(4)
	v_pk_fma_f32 v[226:227], v[226:227], v[214:215], v[192:193]
	v_pk_fma_f32 v[228:229], v[228:229], v[216:217], v[194:195]
	global_store_dwordx4 v211, v[226:229], s[76:77]
	global_load_dwordx4 v[192:195], v211, s[74:75] offset:512 nt
	ds_write_b128 v207, v[76:79]
	ds_write_b128 v208, v[72:75]
	ds_read_b128 v[222:225], v209
	ds_read_b128 v[226:229], v209 offset:8192
	s_waitcnt vmcnt(10) lgkmcnt(5)
	v_pk_fma_f32 v[230:231], v[230:231], v[218:219], v[196:197]
	v_pk_fma_f32 v[232:233], v[232:233], v[220:221], v[198:199]
	global_store_dwordx4 v210, v[230:233], s[76:77] offset:512
	s_add_u32 s74, s74, 0x10000
	s_addc_u32 s75, s75, 0
	global_load_dwordx4 v[196:199], v210, s[74:75] nt
	s_waitcnt vmcnt(10) lgkmcnt(4)
	v_pk_fma_f32 v[234:235], v[234:235], v[218:219], v[186:187]
	v_pk_fma_f32 v[236:237], v[236:237], v[220:221], v[188:189]
	global_store_dwordx4 v211, v[234:237], s[76:77] offset:512
	global_load_dwordx4 v[186:189], v211, s[74:75] nt
	ds_write_b128 v207, v[12:15]
	ds_write_b128 v208, v[8:11]
	ds_read_b128 v[230:233], v209
	ds_read_b128 v[234:237], v209 offset:8192
	s_waitcnt vmcnt(10) lgkmcnt(5)
	v_pk_fma_f32 v[222:223], v[222:223], v[214:215], v[238:239]
	v_pk_fma_f32 v[224:225], v[224:225], v[216:217], v[240:241]
	s_add_u32 s76, s76, 0x10000
	s_addc_u32 s77, s77, 0
	global_store_dwordx4 v210, v[222:225], s[76:77]
	global_load_dwordx4 v[238:241], v210, s[74:75] offset:512 nt
	s_waitcnt vmcnt(10) lgkmcnt(4)
	v_pk_fma_f32 v[226:227], v[226:227], v[214:215], v[242:243]
	v_pk_fma_f32 v[228:229], v[228:229], v[216:217], v[244:245]
	global_store_dwordx4 v211, v[226:229], s[76:77]
	global_load_dwordx4 v[242:245], v211, s[74:75] offset:512 nt
	ds_write_b128 v207, v[68:71]
	ds_write_b128 v208, v[64:67]
	ds_read_b128 v[222:225], v209
	ds_read_b128 v[226:229], v209 offset:8192
	s_waitcnt vmcnt(10) lgkmcnt(5)
	v_pk_fma_f32 v[230:231], v[230:231], v[218:219], v[246:247]
	v_pk_fma_f32 v[232:233], v[232:233], v[220:221], v[248:249]
	global_store_dwordx4 v210, v[230:233], s[76:77] offset:512
	s_waitcnt vmcnt(9) lgkmcnt(4)
	v_pk_fma_f32 v[234:235], v[234:235], v[218:219], v[192:193]
	v_pk_fma_f32 v[236:237], v[236:237], v[220:221], v[194:195]
	global_store_dwordx4 v211, v[234:237], s[76:77] offset:512
	ds_write_b128 v207, v[4:7]
	ds_write_b128 v208, v[0:3]
	ds_read_b128 v[230:233], v209
	ds_read_b128 v[234:237], v209 offset:8192
	s_waitcnt vmcnt(8) lgkmcnt(5)
	v_pk_fma_f32 v[222:223], v[222:223], v[214:215], v[196:197]
	v_pk_fma_f32 v[224:225], v[224:225], v[216:217], v[198:199]
	s_add_u32 s76, s76, 0x10000
	s_addc_u32 s77, s77, 0
	global_store_dwordx4 v210, v[222:225], s[76:77]
	s_waitcnt vmcnt(7) lgkmcnt(4)
	v_pk_fma_f32 v[226:227], v[226:227], v[214:215], v[186:187]
	v_pk_fma_f32 v[228:229], v[228:229], v[216:217], v[188:189]
	global_store_dwordx4 v211, v[226:229], s[76:77]
	s_waitcnt vmcnt(6) lgkmcnt(1)
	v_pk_fma_f32 v[230:231], v[230:231], v[218:219], v[238:239]
	v_pk_fma_f32 v[232:233], v[232:233], v[220:221], v[240:241]
	global_store_dwordx4 v210, v[230:233], s[76:77] offset:512
	s_waitcnt vmcnt(5) lgkmcnt(0)
	v_pk_fma_f32 v[234:235], v[234:235], v[218:219], v[242:243]
	v_pk_fma_f32 v[236:237], v[236:237], v[220:221], v[244:245]
	global_store_dwordx4 v211, v[234:237], s[76:77] offset:512
	s_andn2_b64 vcc, exec, s[8:9]
	s_mov_b64 s[0:1], -1
	s_cbranch_vccnz .LBB0_976
	s_branch .Lepi_m2_after
